# v_c11 + attention: waves 4-7 (idle during the epilogue) prefetch the second half's Q rows and first K/V tile into L2
# speedup vs baseline: 1.0003x; 1.0003x over previous
; #define LAS __attribute__((address_space(3)))
; __device__ __forceinline__ void attn_phase(LAS unsigned char* lds, const bf16* PROJ, bf16* MIX, const float* lq1, const float* lk1, const float* lq2, const float* lk2,
;                                            const float* norm_g, float lambda_init, int G, int wave_s) {
;     ...
;             __syncthreads();
;             if (mi == 1) {
; #pragma unroll
;                 for (int mt = 0; mt < 16; ++mt) *(LAS f32x4*)(XCH + ((wq * 16 + mt) * 64 + lane) * 16) = O[mt] * inv;
;             }
;             __syncthreads();
;             if (mi == 0) {
;                 float ss = 0.f;
; #pragma unroll
;                 for (int mt = 0; mt < 16; ++mt) { const f32x4 o1 = *(const LAS f32x4*)(XCH + ((wq * 16 + mt) * 64 + lane) * 16); const f32x4 o = O[mt] * inv - lam * o1; O[mt] = o;
;                     ss += (o.x * o.x + o.y * o.y) + (o.z * o.z + o.w * o.w); }
.LBB0_903:
	s_andn2_b64 vcc, exec, s[14:15]
	s_waitcnt lgkmcnt(0)
	s_barrier
	s_cbranch_vccz .Lattn_pf2_map0
	s_and_b64 vcc, exec, s[20:21]
	s_cbranch_vccnz .LBB0_883
	s_mul_i32 s100, s78, 0xc0000
	s_add_u32 s100, s79, s100
	s_addc_u32 s101, s82, 0
	s_add_u32 s100, s100, 0x1800
	s_addc_u32 s101, s101, 0
	v_mbcnt_lo_u32_b32 v0, -1, 0
	v_mbcnt_hi_u32_b32 v0, -1, v0
	v_add_u32_e32 v0, s89, v0
	v_subrev_u32_e32 v0, 0x100, v0
	v_mov_b32_e32 v2, v0
	v_mul_u32_u24_e32 v3, 0xaaab, v2
	v_lshrrev_b32_e32 v3, 19, v3
	v_mul_u32_u24_e32 v4, 12, v3
	v_sub_u32_e32 v2, v2, v4
	v_mul_u32_u24_e32 v3, 0x3000, v3
	v_lshl_add_u32 v3, v2, 7, v3
	v_lshrrev_b32_e32 v2, 2, v2
	v_mul_u32_u24_e32 v2, 0x600, v2
	v_add_u32_e32 v3, v3, v2
	global_load_dword v250, v3, s[100:101]
	v_add_u32_e32 v2, 0x100, v0
	v_mul_u32_u24_e32 v3, 0xaaab, v2
	v_lshrrev_b32_e32 v3, 19, v3
	v_mul_u32_u24_e32 v4, 12, v3
	v_sub_u32_e32 v2, v2, v4
	v_mul_u32_u24_e32 v3, 0x3000, v3
	v_lshl_add_u32 v3, v2, 7, v3
	v_lshrrev_b32_e32 v2, 2, v2
	v_mul_u32_u24_e32 v2, 0x600, v2
	v_add_u32_e32 v3, v3, v2
	global_load_dword v250, v3, s[100:101]
	v_add_u32_e32 v2, 0x200, v0
	v_mul_u32_u24_e32 v3, 0xaaab, v2
	v_lshrrev_b32_e32 v3, 19, v3
	v_mul_u32_u24_e32 v4, 12, v3
	v_sub_u32_e32 v2, v2, v4
	v_mul_u32_u24_e32 v3, 0x3000, v3
	v_lshl_add_u32 v3, v2, 7, v3
	v_lshrrev_b32_e32 v2, 2, v2
	v_mul_u32_u24_e32 v2, 0x600, v2
	v_add_u32_e32 v3, v3, v2
	global_load_dword v250, v3, s[100:101]
	s_branch .LBB0_883
.Lattn_pf2_map0:
	ds_read_b128 v[70:73], v68
	s_waitcnt lgkmcnt(0)
	v_pk_mul_f32 v[66:67], v[152:153], v[72:73]
	v_pk_mul_f32 v[70:71], v[150:151], v[70:71]
	v_pk_fma_f32 v[64:65], v[64:65], v[0:1], v[66:67] op_sel_hi:[1,0,1] neg_lo:[0,0,1] neg_hi:[0,0,1]
	v_pk_fma_f32 v[66:67], v[62:63], v[0:1], v[70:71] op_sel_hi:[1,0,1] neg_lo:[0,0,1] neg_hi:[0,0,1]
	ds_read_b128 v[70:73], v68 offset:1024
	v_mul_f32_e32 v62, v67, v67
	v_mul_f32_e32 v63, v65, v65
	v_fmac_f32_e32 v62, v66, v66
	v_fmac_f32_e32 v63, v64, v64
	v_add_f32_e32 v69, v62, v63
	s_waitcnt lgkmcnt(0)
	v_pk_mul_f32 v[62:63], v[152:153], v[72:73]
	v_pk_mul_f32 v[70:71], v[150:151], v[70:71]
	v_pk_fma_f32 v[60:61], v[60:61], v[0:1], v[62:63] op_sel_hi:[1,0,1] neg_lo:[0,0,1] neg_hi:[0,0,1]
	v_pk_fma_f32 v[62:63], v[58:59], v[0:1], v[70:71] op_sel_hi:[1,0,1] neg_lo:[0,0,1] neg_hi:[0,0,1]
	ds_read_b128 v[70:73], v68 offset:2048
	v_mul_f32_e32 v58, v63, v63
	v_mul_f32_e32 v59, v61, v61
	v_fmac_f32_e32 v58, v62, v62
	v_fmac_f32_e32 v59, v60, v60
	v_add_f32_e32 v58, v58, v59
	v_add_f32_e32 v69, v69, v58
	s_waitcnt lgkmcnt(0)
	v_pk_mul_f32 v[58:59], v[152:153], v[72:73]
	v_pk_mul_f32 v[70:71], v[150:151], v[70:71]
	v_pk_fma_f32 v[56:57], v[56:57], v[0:1], v[58:59] op_sel_hi:[1,0,1] neg_lo:[0,0,1] neg_hi:[0,0,1]
	v_pk_fma_f32 v[58:59], v[54:55], v[0:1], v[70:71] op_sel_hi:[1,0,1] neg_lo:[0,0,1] neg_hi:[0,0,1]
	ds_read_b128 v[70:73], v68 offset:3072
	v_mul_f32_e32 v54, v59, v59
	v_mul_f32_e32 v55, v57, v57
	v_fmac_f32_e32 v54, v58, v58
	v_fmac_f32_e32 v55, v56, v56
	v_add_f32_e32 v54, v54, v55
	v_add_f32_e32 v69, v69, v54
	s_waitcnt lgkmcnt(0)
	v_pk_mul_f32 v[54:55], v[152:153], v[72:73]
	v_pk_mul_f32 v[70:71], v[150:151], v[70:71]
	v_pk_fma_f32 v[52:53], v[52:53], v[0:1], v[54:55] op_sel_hi:[1,0,1] neg_lo:[0,0,1] neg_hi:[0,0,1]
	v_pk_fma_f32 v[54:55], v[50:51], v[0:1], v[70:71] op_sel_hi:[1,0,1] neg_lo:[0,0,1] neg_hi:[0,0,1]
	ds_read_b128 v[70:73], v68 offset:4096
	v_mul_f32_e32 v50, v55, v55
	v_mul_f32_e32 v51, v53, v53
	v_fmac_f32_e32 v50, v54, v54
	v_fmac_f32_e32 v51, v52, v52
	v_add_f32_e32 v50, v50, v51
	v_add_f32_e32 v69, v69, v50
	s_waitcnt lgkmcnt(0)
	v_pk_mul_f32 v[50:51], v[152:153], v[72:73]
	v_pk_mul_f32 v[70:71], v[150:151], v[70:71]
	v_pk_fma_f32 v[48:49], v[48:49], v[0:1], v[50:51] op_sel_hi:[1,0,1] neg_lo:[0,0,1] neg_hi:[0,0,1]
	v_pk_fma_f32 v[50:51], v[46:47], v[0:1], v[70:71] op_sel_hi:[1,0,1] neg_lo:[0,0,1] neg_hi:[0,0,1]
	ds_read_b128 v[70:73], v68 offset:5120
	v_mul_f32_e32 v46, v51, v51
	v_mul_f32_e32 v47, v49, v49
	v_fmac_f32_e32 v46, v50, v50
	v_fmac_f32_e32 v47, v48, v48
	v_add_f32_e32 v46, v46, v47
	v_add_f32_e32 v69, v69, v46
	s_waitcnt lgkmcnt(0)
	v_pk_mul_f32 v[46:47], v[152:153], v[72:73]
	v_pk_mul_f32 v[70:71], v[150:151], v[70:71]
	v_pk_fma_f32 v[44:45], v[44:45], v[0:1], v[46:47] op_sel_hi:[1,0,1] neg_lo:[0,0,1] neg_hi:[0,0,1]
	v_pk_fma_f32 v[46:47], v[42:43], v[0:1], v[70:71] op_sel_hi:[1,0,1] neg_lo:[0,0,1] neg_hi:[0,0,1]
	ds_read_b128 v[70:73], v68 offset:6144
	v_mul_f32_e32 v42, v47, v47
	v_mul_f32_e32 v43, v45, v45
	v_fmac_f32_e32 v42, v46, v46
	v_fmac_f32_e32 v43, v44, v44
	v_add_f32_e32 v42, v42, v43
	v_add_f32_e32 v69, v69, v42
	s_waitcnt lgkmcnt(0)
	v_pk_mul_f32 v[42:43], v[152:153], v[72:73]
	v_pk_mul_f32 v[70:71], v[150:151], v[70:71]
	v_pk_fma_f32 v[40:41], v[40:41], v[0:1], v[42:43] op_sel_hi:[1,0,1] neg_lo:[0,0,1] neg_hi:[0,0,1]
	v_pk_fma_f32 v[42:43], v[38:39], v[0:1], v[70:71] op_sel_hi:[1,0,1] neg_lo:[0,0,1] neg_hi:[0,0,1]
	ds_read_b128 v[70:73], v68 offset:7168
	v_mul_f32_e32 v38, v43, v43
	v_mul_f32_e32 v39, v41, v41
	v_fmac_f32_e32 v38, v42, v42
	v_fmac_f32_e32 v39, v40, v40
	v_add_f32_e32 v38, v38, v39
	v_add_f32_e32 v69, v69, v38
	s_waitcnt lgkmcnt(0)
	v_pk_mul_f32 v[38:39], v[152:153], v[72:73]
	v_pk_mul_f32 v[70:71], v[150:151], v[70:71]
	v_pk_fma_f32 v[36:37], v[36:37], v[0:1], v[38:39] op_sel_hi:[1,0,1] neg_lo:[0,0,1] neg_hi:[0,0,1]
	v_pk_fma_f32 v[38:39], v[34:35], v[0:1], v[70:71] op_sel_hi:[1,0,1] neg_lo:[0,0,1] neg_hi:[0,0,1]
	ds_read_b128 v[70:73], v68 offset:8192
	v_mul_f32_e32 v34, v39, v39
	v_mul_f32_e32 v35, v37, v37
	v_fmac_f32_e32 v34, v38, v38
	v_fmac_f32_e32 v35, v36, v36
	v_add_f32_e32 v34, v34, v35
	v_add_f32_e32 v69, v69, v34
	s_waitcnt lgkmcnt(0)
; __device__ __forceinline__ float xor16_sum(float v) { const auto r = __builtin_amdgcn_permlane16_swap(__float_as_uint(v), __float_as_uint(v), false, false); return __uint_as_float(r[0]) + __uint_as_float(r[1]); }
; __device__ __forceinline__ float xor32_sum(float v) { const auto r = __builtin_amdgcn_permlane32_swap(__float_as_uint(v), __float_as_uint(v), false, false); return __uint_as_float(r[0]) + __uint_as_float(r[1]); }
; #define LAS __attribute__((address_space(3)))
; __device__ __forceinline__ void attn_phase(LAS unsigned char* lds, const bf16* PROJ, bf16* MIX, const float* lq1, const float* lk1, const float* lq2, const float* lk2,
;                                            const float* norm_g, float lambda_init, int G, int wave_s) {
;     ...
;                 for (int mt = 0; mt < 16; ++mt) { const f32x4 o1 = *(const LAS f32x4*)(XCH + ((wq * 16 + mt) * 64 + lane) * 16); const f32x4 o = O[mt] * inv - lam * o1; O[mt] = o;
;                     ss += (o.x * o.x + o.y * o.y) + (o.z * o.z + o.w * o.w); }
;                 ss = xor32_sum(xor16_sum(ss));
;                 const float rs = __builtin_amdgcn_rsqf(ss * (1.0f / 256.0f) + LN_EPS) * (1.0f - lambda_init);
;                 bf16* orow = MIX + (size_t)(b * SEQ + 64 * qb + qloc) * DM + 1024 + h * 256 + 4 * q4;
; #pragma unroll
;                 for (int mt = 0; mt < 16; ++mt) { const f32x4 g = *(const f32x4*)(norm_g + 16 * mt + 4 * q4); const f32x4 o = O[mt] * rs * g;
	v_pk_mul_f32 v[34:35], v[152:153], v[72:73]
	v_pk_mul_f32 v[70:71], v[150:151], v[70:71]
	v_pk_fma_f32 v[32:33], v[32:33], v[0:1], v[34:35] op_sel_hi:[1,0,1] neg_lo:[0,0,1] neg_hi:[0,0,1]
	v_pk_fma_f32 v[34:35], v[30:31], v[0:1], v[70:71] op_sel_hi:[1,0,1] neg_lo:[0,0,1] neg_hi:[0,0,1]
	ds_read_b128 v[70:73], v68 offset:9216
	v_mul_f32_e32 v30, v35, v35
	v_mul_f32_e32 v31, v33, v33
	v_fmac_f32_e32 v30, v34, v34
	v_fmac_f32_e32 v31, v32, v32
	v_add_f32_e32 v30, v30, v31
	v_add_f32_e32 v69, v69, v30
	s_waitcnt lgkmcnt(0)
	v_pk_mul_f32 v[30:31], v[152:153], v[72:73]
	v_pk_mul_f32 v[70:71], v[150:151], v[70:71]
	v_pk_fma_f32 v[28:29], v[28:29], v[0:1], v[30:31] op_sel_hi:[1,0,1] neg_lo:[0,0,1] neg_hi:[0,0,1]
	v_pk_fma_f32 v[30:31], v[26:27], v[0:1], v[70:71] op_sel_hi:[1,0,1] neg_lo:[0,0,1] neg_hi:[0,0,1]
	ds_read_b128 v[70:73], v68 offset:10240
	v_mul_f32_e32 v26, v31, v31
	v_mul_f32_e32 v27, v29, v29
	v_fmac_f32_e32 v26, v30, v30
	v_fmac_f32_e32 v27, v28, v28
	v_add_f32_e32 v26, v26, v27
	v_add_f32_e32 v69, v69, v26
	s_waitcnt lgkmcnt(0)
	v_pk_mul_f32 v[26:27], v[152:153], v[72:73]
	v_pk_mul_f32 v[70:71], v[150:151], v[70:71]
	v_pk_fma_f32 v[24:25], v[24:25], v[0:1], v[26:27] op_sel_hi:[1,0,1] neg_lo:[0,0,1] neg_hi:[0,0,1]
	v_pk_fma_f32 v[26:27], v[22:23], v[0:1], v[70:71] op_sel_hi:[1,0,1] neg_lo:[0,0,1] neg_hi:[0,0,1]
	ds_read_b128 v[70:73], v68 offset:11264
	v_mul_f32_e32 v22, v27, v27
	v_mul_f32_e32 v23, v25, v25
	v_fmac_f32_e32 v22, v26, v26
	v_fmac_f32_e32 v23, v24, v24
	v_add_f32_e32 v22, v22, v23
	v_add_f32_e32 v69, v69, v22
	s_waitcnt lgkmcnt(0)
	v_pk_mul_f32 v[22:23], v[152:153], v[72:73]
	v_pk_mul_f32 v[70:71], v[150:151], v[70:71]
	v_pk_fma_f32 v[16:17], v[16:17], v[0:1], v[22:23] op_sel_hi:[1,0,1] neg_lo:[0,0,1] neg_hi:[0,0,1]
	v_pk_fma_f32 v[22:23], v[14:15], v[0:1], v[70:71] op_sel_hi:[1,0,1] neg_lo:[0,0,1] neg_hi:[0,0,1]
	ds_read_b128 v[70:73], v68 offset:12288
	v_mul_f32_e32 v14, v23, v23
	v_mul_f32_e32 v15, v17, v17
	v_fmac_f32_e32 v14, v22, v22
	v_fmac_f32_e32 v15, v16, v16
	v_add_f32_e32 v14, v14, v15
	s_waitcnt lgkmcnt(0)
	v_pk_mul_f32 v[70:71], v[150:151], v[70:71]
	v_add_f32_e32 v69, v69, v14
	v_pk_mul_f32 v[14:15], v[152:153], v[72:73]
	v_pk_fma_f32 v[18:19], v[18:19], v[0:1], v[70:71] op_sel_hi:[1,0,1] neg_lo:[0,0,1] neg_hi:[0,0,1]
	ds_read_b128 v[70:73], v68 offset:13312
	v_pk_fma_f32 v[14:15], v[20:21], v[0:1], v[14:15] op_sel_hi:[1,0,1] neg_lo:[0,0,1] neg_hi:[0,0,1]
	v_mul_f32_e32 v20, v19, v19
	v_mul_f32_e32 v21, v15, v15
	v_fmac_f32_e32 v20, v18, v18
	v_fmac_f32_e32 v21, v14, v14
	v_add_f32_e32 v20, v20, v21
	v_add_f32_e32 v69, v69, v20
	s_waitcnt lgkmcnt(0)
	v_pk_mul_f32 v[20:21], v[152:153], v[72:73]
	v_pk_mul_f32 v[70:71], v[150:151], v[70:71]
	v_pk_fma_f32 v[12:13], v[12:13], v[0:1], v[20:21] op_sel_hi:[1,0,1] neg_lo:[0,0,1] neg_hi:[0,0,1]
	v_pk_fma_f32 v[10:11], v[10:11], v[0:1], v[70:71] op_sel_hi:[1,0,1] neg_lo:[0,0,1] neg_hi:[0,0,1]
	v_mul_f32_e32 v21, v13, v13
	v_mul_f32_e32 v20, v11, v11
	v_fmac_f32_e32 v20, v10, v10
	v_fmac_f32_e32 v21, v12, v12
	v_add_f32_e32 v20, v20, v21
	v_add_f32_e32 v72, v69, v20
	ds_read_b128 v[68:71], v68 offset:14336
	s_waitcnt lgkmcnt(0)
	v_pk_mul_f32 v[20:21], v[152:153], v[70:71]
	v_pk_mul_f32 v[68:69], v[150:151], v[68:69]
	v_pk_fma_f32 v[8:9], v[8:9], v[0:1], v[20:21] op_sel_hi:[1,0,1] neg_lo:[0,0,1] neg_hi:[0,0,1]
	v_pk_fma_f32 v[6:7], v[6:7], v[0:1], v[68:69] op_sel_hi:[1,0,1] neg_lo:[0,0,1] neg_hi:[0,0,1]
	v_mul_f32_e32 v21, v9, v9
	v_mul_f32_e32 v20, v7, v7
	v_fmac_f32_e32 v20, v6, v6
	v_fmac_f32_e32 v21, v8, v8
	v_add_f32_e32 v20, v20, v21
	v_add_f32_e32 v72, v72, v20
	v_add_u32_e32 v20, s73, v170
	ds_read_b128 v[68:71], v20
	s_waitcnt lgkmcnt(0)
	v_pk_mul_f32 v[20:21], v[152:153], v[70:71]
	v_pk_mul_f32 v[68:69], v[150:151], v[68:69]
	v_pk_fma_f32 v[20:21], v[4:5], v[0:1], v[20:21] op_sel_hi:[1,0,1] neg_lo:[0,0,1] neg_hi:[0,0,1]
	v_pk_fma_f32 v[68:69], v[2:3], v[0:1], v[68:69] op_sel_hi:[1,0,1] neg_lo:[0,0,1] neg_hi:[0,0,1]
	v_mul_f32_e32 v2, v21, v21
	v_mul_f32_e32 v0, v69, v69
	v_fmac_f32_e32 v0, v68, v68
	v_fmac_f32_e32 v2, v20, v20
	v_add_f32_e32 v0, v0, v2
	v_add_f32_e32 v0, v72, v0
	v_mov_b32_e32 v2, v0
	s_nop 1
	v_permlane16_swap_b32_e32 v0, v2
	v_add_f32_e32 v0, v0, v2
	v_mov_b32_e32 v2, v0
	s_nop 1
	v_permlane32_swap_b32_e32 v0, v2
	v_add_f32_e32 v0, v0, v2
	v_or_b32_e32 v2, s85, v214
	v_ashrrev_i32_e32 v3, 31, v2
	v_lshlrev_b64 v[2:3], 12, v[2:3]
	v_lshl_add_u64 v[70:71], v[160:161], 0, v[2:3]
	global_load_dwordx4 v[82:85], v[154:155], off
	global_load_dwordx4 v[86:89], v[154:155], off offset:64
	global_load_dwordx4 v[90:93], v[154:155], off offset:128
	global_load_dwordx4 v[94:97], v[154:155], off offset:192
	global_load_dwordx4 v[98:101], v[154:155], off offset:256
	global_load_dwordx4 v[102:105], v[154:155], off offset:320
	global_load_dwordx4 v[106:109], v[154:155], off offset:384
	global_load_dwordx4 v[110:113], v[154:155], off offset:448
	global_load_dwordx4 v[114:117], v[154:155], off offset:512
	global_load_dwordx4 v[118:121], v[154:155], off offset:576
	global_load_dwordx4 v[122:125], v[154:155], off offset:640
	global_load_dwordx4 v[126:129], v[154:155], off offset:704
	global_load_dwordx4 v[130:133], v[154:155], off offset:768
	global_load_dwordx4 v[134:137], v[154:155], off offset:832
	global_load_dwordx4 v[228:231], v[154:155], off offset:896
	global_load_dwordx4 v[232:235], v[154:155], off offset:960
	v_fmamk_f32 v0, v0, 0x3b800000, v216
	v_rsq_f32_e32 v0, v0
	s_nop 0
	v_mul_f32_e32 v0, v171, v0
	v_pk_mul_f32 v[66:67], v[66:67], v[0:1] op_sel_hi:[1,0]
	v_pk_mul_f32 v[64:65], v[64:65], v[0:1] op_sel_hi:[1,0]
; __device__ __forceinline__ unsigned pk2(float lo, float hi) { const f32x2 v = {lo, hi}; const bf16x2_n b = __builtin_convertvector(v, bf16x2_n); return __builtin_bit_cast(unsigned, b); }
; __device__ __forceinline__ void attn_phase(LAS unsigned char* lds, const bf16* PROJ, bf16* MIX, const float* lq1, const float* lk1, const float* lq2, const float* lk2,
;                                            const float* norm_g, float lambda_init, int G, int wave_s) {
;     ...
;                 const float rs = __builtin_amdgcn_rsqf(ss * (1.0f / 256.0f) + LN_EPS) * (1.0f - lambda_init);
;                 bf16* orow = MIX + (size_t)(b * SEQ + 64 * qb + qloc) * DM + 1024 + h * 256 + 4 * q4;
; #pragma unroll
;                 for (int mt = 0; mt < 16; ++mt) { const f32x4 g = *(const f32x4*)(norm_g + 16 * mt + 4 * q4); const f32x4 o = O[mt] * rs * g;
;                     v2u wv; wv.x = pk2(o.x, o.y); wv.y = pk2(o.z, o.w); *(v2u*)(orow + 16 * mt) = wv; }
	v_pk_mul_f32 v[62:63], v[62:63], v[0:1] op_sel_hi:[1,0]
	v_pk_mul_f32 v[60:61], v[60:61], v[0:1] op_sel_hi:[1,0]
	v_pk_mul_f32 v[58:59], v[58:59], v[0:1] op_sel_hi:[1,0]
	v_pk_mul_f32 v[56:57], v[56:57], v[0:1] op_sel_hi:[1,0]
	v_pk_mul_f32 v[54:55], v[54:55], v[0:1] op_sel_hi:[1,0]
	v_pk_mul_f32 v[52:53], v[52:53], v[0:1] op_sel_hi:[1,0]
	v_pk_mul_f32 v[50:51], v[50:51], v[0:1] op_sel_hi:[1,0]
	v_pk_mul_f32 v[48:49], v[48:49], v[0:1] op_sel_hi:[1,0]
	v_pk_mul_f32 v[46:47], v[46:47], v[0:1] op_sel_hi:[1,0]
	v_pk_mul_f32 v[44:45], v[44:45], v[0:1] op_sel_hi:[1,0]
	v_pk_mul_f32 v[42:43], v[42:43], v[0:1] op_sel_hi:[1,0]
	v_pk_mul_f32 v[40:41], v[40:41], v[0:1] op_sel_hi:[1,0]
	v_pk_mul_f32 v[38:39], v[38:39], v[0:1] op_sel_hi:[1,0]
	v_pk_mul_f32 v[36:37], v[36:37], v[0:1] op_sel_hi:[1,0]
	v_pk_mul_f32 v[34:35], v[34:35], v[0:1] op_sel_hi:[1,0]
	v_pk_mul_f32 v[32:33], v[32:33], v[0:1] op_sel_hi:[1,0]
	v_pk_mul_f32 v[30:31], v[30:31], v[0:1] op_sel_hi:[1,0]
	v_pk_mul_f32 v[28:29], v[28:29], v[0:1] op_sel_hi:[1,0]
	v_pk_mul_f32 v[26:27], v[26:27], v[0:1] op_sel_hi:[1,0]
	v_pk_mul_f32 v[24:25], v[24:25], v[0:1] op_sel_hi:[1,0]
	v_pk_mul_f32 v[22:23], v[22:23], v[0:1] op_sel_hi:[1,0]
	v_pk_mul_f32 v[16:17], v[16:17], v[0:1] op_sel_hi:[1,0]
	v_pk_mul_f32 v[14:15], v[14:15], v[0:1] op_sel_hi:[1,0]
	v_pk_mul_f32 v[10:11], v[10:11], v[0:1] op_sel_hi:[1,0]
	v_pk_mul_f32 v[12:13], v[12:13], v[0:1] op_sel_hi:[1,0]
	v_pk_mul_f32 v[6:7], v[6:7], v[0:1] op_sel_hi:[1,0]
	v_pk_mul_f32 v[8:9], v[8:9], v[0:1] op_sel_hi:[1,0]
	s_waitcnt vmcnt(0)
	v_pk_mul_f32 v[4:5], v[84:85], v[64:65]
	v_pk_mul_f32 v[2:3], v[82:83], v[66:67]
	v_mbcnt_lo_u32_b32 v66, -1, 0
	v_mbcnt_hi_u32_b32 v66, -1, v66
	v_bfe_u32 v66, v66, 4, 1
	v_mul_u32_u24_e32 v66, 24, v66
	v_mov_b32_e32 v67, 0
	v_lshl_add_u64 v[66:67], v[70:71], 0, v[66:67]
	s_nop 0
	v_cvt_pk_bf16_f32 v2, v2, v3
	v_cvt_pk_bf16_f32 v3, v4, v5
	v_pk_mul_f32 v[84:85], v[88:89], v[60:61]
	v_pk_mul_f32 v[82:83], v[86:87], v[62:63]
	s_nop 0
	v_cvt_pk_bf16_f32 v4, v82, v83
	v_cvt_pk_bf16_f32 v5, v84, v85
	s_nop 1
	v_permlane16_swap_b32_e32 v2, v4
	v_permlane16_swap_b32_e32 v3, v5
	global_store_dwordx4 v[66:67], v[2:5], off offset:2048
	s_nop 1
	v_pk_mul_f32 v[4:5], v[92:93], v[56:57]
	v_pk_mul_f32 v[2:3], v[90:91], v[58:59]
	s_nop 0
	v_cvt_pk_bf16_f32 v2, v2, v3
	v_cvt_pk_bf16_f32 v3, v4, v5
	v_pk_mul_f32 v[92:93], v[96:97], v[52:53]
	v_pk_mul_f32 v[90:91], v[94:95], v[54:55]
	s_nop 0
	v_cvt_pk_bf16_f32 v4, v90, v91
	v_cvt_pk_bf16_f32 v5, v92, v93
	s_nop 1
	v_permlane16_swap_b32_e32 v2, v4
	v_permlane16_swap_b32_e32 v3, v5
	global_store_dwordx4 v[66:67], v[2:5], off offset:2112
	s_nop 1
	v_pk_mul_f32 v[4:5], v[100:101], v[48:49]
	v_pk_mul_f32 v[2:3], v[98:99], v[50:51]
	s_nop 0
	v_cvt_pk_bf16_f32 v2, v2, v3
	v_cvt_pk_bf16_f32 v3, v4, v5
	v_pk_mul_f32 v[100:101], v[44:45], v[104:105]
	v_pk_mul_f32 v[98:99], v[46:47], v[102:103]
	s_nop 0
	v_cvt_pk_bf16_f32 v4, v98, v99
	v_cvt_pk_bf16_f32 v5, v100, v101
	s_nop 1
	v_permlane16_swap_b32_e32 v2, v4
	v_permlane16_swap_b32_e32 v3, v5
	global_store_dwordx4 v[66:67], v[2:5], off offset:2176
	s_nop 1
	v_pk_mul_f32 v[4:5], v[40:41], v[108:109]
	v_pk_mul_f32 v[2:3], v[42:43], v[106:107]
	s_nop 0
	v_cvt_pk_bf16_f32 v2, v2, v3
	v_cvt_pk_bf16_f32 v3, v4, v5
	v_pk_mul_f32 v[108:109], v[36:37], v[112:113]
	v_pk_mul_f32 v[106:107], v[38:39], v[110:111]
	s_nop 0
	v_cvt_pk_bf16_f32 v4, v106, v107
	v_cvt_pk_bf16_f32 v5, v108, v109
	s_nop 1
	v_permlane16_swap_b32_e32 v2, v4
	v_permlane16_swap_b32_e32 v3, v5
	global_store_dwordx4 v[66:67], v[2:5], off offset:2240
	s_nop 1
	v_pk_mul_f32 v[4:5], v[32:33], v[116:117]
	v_pk_mul_f32 v[2:3], v[34:35], v[114:115]
	s_nop 0
	v_cvt_pk_bf16_f32 v2, v2, v3
	v_cvt_pk_bf16_f32 v3, v4, v5
	v_pk_mul_f32 v[116:117], v[28:29], v[120:121]
	v_pk_mul_f32 v[114:115], v[30:31], v[118:119]
	s_nop 0
	v_cvt_pk_bf16_f32 v4, v114, v115
	v_cvt_pk_bf16_f32 v5, v116, v117
	s_nop 1
	v_permlane16_swap_b32_e32 v2, v4
	v_permlane16_swap_b32_e32 v3, v5
	global_store_dwordx4 v[66:67], v[2:5], off offset:2304
	s_nop 1
	v_pk_mul_f32 v[4:5], v[24:25], v[124:125]
	v_pk_mul_f32 v[2:3], v[26:27], v[122:123]
	s_nop 0
	v_cvt_pk_bf16_f32 v2, v2, v3
	v_cvt_pk_bf16_f32 v3, v4, v5
	v_pk_mul_f32 v[124:125], v[16:17], v[128:129]
	v_pk_mul_f32 v[122:123], v[22:23], v[126:127]
	v_pk_mul_f32 v[16:17], v[18:19], v[0:1] op_sel_hi:[1,0]
	v_cvt_pk_bf16_f32 v4, v122, v123
	v_cvt_pk_bf16_f32 v5, v124, v125
	s_nop 1
	v_permlane16_swap_b32_e32 v2, v4
	v_permlane16_swap_b32_e32 v3, v5
	global_store_dwordx4 v[66:67], v[2:5], off offset:2368
	s_nop 1
	v_pk_mul_f32 v[4:5], v[14:15], v[132:133]
	v_pk_mul_f32 v[2:3], v[16:17], v[130:131]
	s_nop 0
	v_cvt_pk_bf16_f32 v2, v2, v3
	v_cvt_pk_bf16_f32 v3, v4, v5
	v_pk_mul_f32 v[132:133], v[12:13], v[136:137]
	v_pk_mul_f32 v[130:131], v[10:11], v[134:135]
	s_nop 0
	v_cvt_pk_bf16_f32 v4, v130, v131
	v_cvt_pk_bf16_f32 v5, v132, v133
	s_nop 1
	v_permlane16_swap_b32_e32 v2, v4
	v_permlane16_swap_b32_e32 v3, v5
	global_store_dwordx4 v[66:67], v[2:5], off offset:2432
	s_nop 1
	v_pk_mul_f32 v[4:5], v[8:9], v[230:231]
	v_pk_mul_f32 v[2:3], v[6:7], v[228:229]
	v_pk_mul_f32 v[6:7], v[68:69], v[0:1] op_sel_hi:[1,0]
	v_cvt_pk_bf16_f32 v2, v2, v3
	v_cvt_pk_bf16_f32 v3, v4, v5
	v_pk_mul_f32 v[8:9], v[20:21], v[0:1] op_sel_hi:[1,0]
	v_pk_mul_f32 v[228:229], v[6:7], v[232:233]
	v_pk_mul_f32 v[230:231], v[8:9], v[234:235]
	v_cvt_pk_bf16_f32 v4, v228, v229
	v_cvt_pk_bf16_f32 v5, v230, v231
	s_nop 1
	v_permlane16_swap_b32_e32 v2, v4
	v_permlane16_swap_b32_e32 v3, v5
	global_store_dwordx4 v[66:67], v[2:5], off offset:2496
	s_nop 1
	s_branch .LBB0_883
